# attention stagger: priority kept at 1 through the first exp group of the PV segment (dropped just before its first MFMA)
# baseline (speedup 1.0000x reference)
; __device__ __forceinline__ s16x4 vtr(const ALDS unsigned char* p) { return __builtin_bit_cast(s16x4, __builtin_amdgcn_ds_read_tr16_b64_v4i16((ALDS s16x4*)p)); }
; template <int DV, bool BAND> ...
;     ...
;         const bool first = (!BAND) && (t == t0);
;         const float dl = first ? mx : ((mx > THR) ? mx : 0.f);
;         if (__any(dl != 0.f)) {
;             m += dl;
; #pragma unroll
;             for (int r = 0; r < 16; ++r) { p0[r] -= dl; p1[r] -= dl; negm[r] = -m; }
;             const float f = first ? 1.f : __builtin_amdgcn_exp2f(-dl);
;             l *= f;
; #pragma unroll
;             for (int db = 0; db < NDB; ++db)
; #pragma unroll
;                 for (int r = 0; r < 16; ++r) o[db][r] *= f;
;         }
;         float ssum = 0.f;
;         bf16x8 pfs[4];
;     ...
;         ATT_EXP_SLICE(p0, 0, pfs[0]);
; #pragma unroll
;         for (int ks = 0; ks < 4; ++ks) {
;             if (ks + 1 < 4) {
; #pragma unroll
;                 for (int db = 0; db < NDB; ++db) { vlo[(ks + 1) & 1][db] = vtr(sb + va[db] + (ks + 1) * (16 * ROWB)); vhh[(ks + 1) & 1][db] = vtr(sb + va[db] + (ks + 1) * (16 * ROWB) + 4 * ROWB); }
;             }
; #pragma unroll
;             for (int db = 0; db < NDB; ++db) {
;                 const s16x4 lo = vlo[ks & 1][db], hh = vhh[ks & 1][db];
;                 const bf16x8 vf = (bf16x8){lo[0], lo[1], lo[2], lo[3], hh[0], hh[1], hh[2], hh[3]};
;                 o[db] = __builtin_amdgcn_mfma_f32_32x32x16_bf16(vf, pfs[ks], o[db], 0, 0, 0);
;             }
;             if (ks == 0) ATT_EXP_SLICE(p0, 8, pfs[1]);
;             if (ks == 1) ATT_EXP_SLICE(p1, 0, pfs[2]);
;             if (ks == 2) ATT_EXP_SLICE(p1, 8, pfs[3]);
.LBB0_773:
	s_waitcnt vmcnt(4)
	s_barrier
	v_exp_f32_e32 v101, v84
	v_exp_f32_e32 v103, v85
	v_exp_f32_e32 v85, v86
	v_exp_f32_e32 v87, v87
	v_exp_f32_e32 v100, v88
	v_exp_f32_e32 v102, v89
	v_exp_f32_e32 v84, v90
	v_exp_f32_e32 v86, v91
	v_cvt_pk_bf16_f32 v88, v101, v103
	v_cvt_pk_bf16_f32 v89, v85, v87
	v_cvt_pk_bf16_f32 v90, v100, v102
	v_cvt_pk_bf16_f32 v91, v84, v86
	ds_read_b64_tr_b16 v[110:111], v108 offset:20480
	ds_read_b64_tr_b16 v[112:113], v108 offset:21504
	ds_read_b64_tr_b16 v[130:131], v107 offset:4096
	ds_read_b64_tr_b16 v[132:133], v107 offset:5120
	ds_read_b64_tr_b16 v[134:135], v106 offset:4096
	ds_read_b64_tr_b16 v[136:137], v106 offset:5120
	ds_read_b64_tr_b16 v[138:139], v67 offset:4096
	ds_read_b64_tr_b16 v[140:141], v67 offset:5120
	s_setprio 0
	s_waitcnt lgkmcnt(14)
	v_mfma_f32_32x32x16_bf16 v[50:65], v[14:17], v[88:91], 0
	v_exp_f32_e32 v105, v92
	v_exp_f32_e32 v93, v93
	v_exp_f32_e32 v104, v94
	v_exp_f32_e32 v92, v95
	ds_read_b64_tr_b16 v[142:143], v108 offset:24576
	ds_read_b64_tr_b16 v[144:145], v108 offset:25600
	ds_read_b64_tr_b16 v[160:161], v107 offset:8192
	ds_read_b64_tr_b16 v[162:163], v107 offset:9216
	ds_read_b64_tr_b16 v[164:165], v106 offset:8192
	ds_read_b64_tr_b16 v[166:167], v106 offset:9216
	ds_read_b64_tr_b16 v[168:169], v67 offset:8192
	ds_read_b64_tr_b16 v[170:171], v67 offset:9216
	v_cvt_pk_bf16_f32 v94, v105, v93
	v_exp_f32_e32 v0, v76
	s_waitcnt lgkmcnt(14)
	v_mfma_f32_32x32x16_bf16 v[34:49], v[10:13], v[88:91], 0
	v_cvt_pk_bf16_f32 v95, v104, v92
	v_exp_f32_e32 v76, v77
	v_exp_f32_e32 v78, v78
	v_exp_f32_e32 v80, v80
	v_exp_f32_e32 v82, v82
	s_mov_b32 s4, 1
	s_mov_b32 s5, 0x18000
	v_mfma_f32_32x32x16_bf16 v[18:33], v[2:5], v[88:91], 0
	s_mov_b32 s6, 0x8000
	s_movk_i32 s49, 0x900
	v_mfma_f32_32x32x16_bf16 v[2:17], v[6:9], v[88:91], 0
	v_exp_f32_e32 v89, v96
	v_exp_f32_e32 v91, v97
	v_exp_f32_e32 v88, v98
	v_exp_f32_e32 v90, v99
	v_exp_f32_e32 v99, v68
	v_cvt_pk_bf16_f32 v96, v89, v91
	v_exp_f32_e32 v98, v79
	v_cvt_pk_bf16_f32 v97, v88, v90
	s_nop 1
	v_mfma_f32_32x32x16_bf16 v[50:65], v[110:113], v[94:97], v[50:65]
	v_exp_f32_e32 v113, v69
	v_exp_f32_e32 v112, v83
	v_cvt_pk_bf16_f32 v68, v99, v113
	s_waitcnt lgkmcnt(12)
	v_mfma_f32_32x32x16_bf16 v[34:49], v[130:133], v[94:97], v[34:49]
	s_waitcnt lgkmcnt(10)
	v_mfma_f32_32x32x16_bf16 v[18:33], v[134:137], v[94:97], v[18:33]
	v_exp_f32_e32 v134, v70
	v_exp_f32_e32 v135, v71
	v_exp_f32_e32 v136, v72
	v_exp_f32_e32 v137, v73
	v_cvt_pk_bf16_f32 v69, v134, v135
	v_cvt_pk_bf16_f32 v70, v136, v137
	s_waitcnt lgkmcnt(8)
	v_mfma_f32_32x32x16_bf16 v[2:17], v[138:141], v[94:97], v[2:17]
	v_exp_f32_e32 v138, v74
	v_exp_f32_e32 v139, v75
	ds_read_b64_tr_b16 v[72:73], v108 offset:28672
	ds_read_b64_tr_b16 v[74:75], v108 offset:29696
	ds_read_b64_tr_b16 v[94:95], v107 offset:12288
	ds_read_b64_tr_b16 v[96:97], v107 offset:13312
	ds_read_b64_tr_b16 v[108:109], v106 offset:12288
	ds_read_b64_tr_b16 v[110:111], v106 offset:13312
	ds_read_b64_tr_b16 v[130:131], v67 offset:12288
	ds_read_b64_tr_b16 v[132:133], v67 offset:13312
	v_exp_f32_e32 v106, v81
	v_add_f32_e32 v81, v113, v99
	v_cvt_pk_bf16_f32 v71, v138, v139
	v_add_f32_e32 v107, v135, v134
	v_add_f32_e32 v83, v137, v136
	s_waitcnt lgkmcnt(14)
	v_mfma_f32_32x32x16_bf16 v[50:65], v[142:145], v[68:71], v[50:65]
	v_add_f32_e32 v113, v139, v138
	v_mov_b32_e32 v67, v66
	s_waitcnt lgkmcnt(12)
	v_mfma_f32_32x32x16_bf16 v[34:49], v[160:163], v[68:71], v[34:49]
	s_waitcnt lgkmcnt(10)
	v_mfma_f32_32x32x16_bf16 v[18:33], v[164:167], v[68:71], v[18:33]
	s_waitcnt lgkmcnt(8)
	v_mfma_f32_32x32x16_bf16 v[2:17], v[168:171], v[68:71], v[2:17]
	v_cvt_pk_bf16_f32 v68, v0, v76
	v_cvt_pk_bf16_f32 v69, v78, v98
	v_cvt_pk_bf16_f32 v70, v80, v106
	v_cvt_pk_bf16_f32 v71, v82, v112
	s_waitcnt lgkmcnt(6)
	s_nop 0
	v_mfma_f32_32x32x16_bf16 v[50:65], v[72:75], v[68:71], v[50:65]
	v_add_f32_e64 v72, v102, v100
	v_add_f32_e64 v73, v103, v101
	v_add_f32_e64 v74, v86, v84
	v_add_f32_e64 v75, v87, v85
	v_add_f32_e64 v72, v74, v72
	v_add_f32_e64 v73, v75, v73
	v_pk_add_f32 v[74:75], v[106:107], v[80:81]
	v_pk_add_f32 v[72:73], v[72:73], v[72:73] op_sel_hi:[0,1]
	v_mov_b32_e32 v77, v73
	s_waitcnt lgkmcnt(4)
	v_mfma_f32_32x32x16_bf16 v[34:49], v[94:97], v[68:71], v[34:49]
	v_add_f32_e64 v80, v112, v82
	v_add_f32_e64 v81, v113, v83
	v_mov_b32_e32 v72, v66
	v_add_f32_e64 v74, v80, v74
	v_add_f32_e64 v75, v81, v75
	v_mov_b32_e32 v73, v66
	v_mov_b32_e32 v80, v66
	v_mov_b32_e32 v81, v66
	s_waitcnt lgkmcnt(2)
	v_mfma_f32_32x32x16_bf16 v[18:33], v[108:111], v[68:71], v[18:33]
	s_waitcnt lgkmcnt(0)
	v_mfma_f32_32x32x16_bf16 v[2:17], v[130:133], v[68:71], v[2:17]
	v_add_f32_e64 v68, v92, v104
	v_add_f32_e64 v69, v93, v105
	v_add_f32_e64 v70, v90, v88
	v_add_f32_e64 v71, v91, v89
	v_pk_add_f32 v[68:69], v[68:69], v[68:69] op_sel_hi:[0,1]
	v_pk_add_f32 v[70:71], v[70:71], v[70:71] op_sel_hi:[0,1]
	v_mov_b32_e32 v99, v71
	v_mov_b32_e32 v79, v69
	v_pk_add_f32 v[68:69], v[98:99], v[78:79]
	v_pk_add_f32 v[70:71], v[76:77], v[0:1]
	v_mov_b32_e32 v76, v66
	v_pk_add_f32 v[68:69], v[68:69], v[70:71]
	v_mov_b32_e32 v70, v66
	v_pk_add_f32 v[68:69], v[74:75], v[68:69]
	v_mov_b32_e32 v71, v66
	v_add_f32_e32 v160, v68, v69
	v_mov_b32_e32 v68, v66
	v_mov_b32_e32 v69, v66
	v_mov_b32_e32 v74, v66
	v_mov_b32_e32 v75, v66
	v_mov_b32_e32 v77, v66
	v_mov_b32_e32 v78, v66
	v_mov_b32_e32 v79, v66
	s_branch .LBB0_775

; __device__ __forceinline__ s16x4 vtr(const ALDS unsigned char* p) { return __builtin_bit_cast(s16x4, __builtin_amdgcn_ds_read_tr16_b64_v4i16((ALDS s16x4*)p)); }
; template <int DV, bool BAND> ...
;     ...
;         float ssum = 0.f;
;         bf16x8 pfs[4];
;     ...
;         ATT_EXP_SLICE(p0, 0, pfs[0]);
; #pragma unroll
;         for (int ks = 0; ks < 4; ++ks) {
;             if (ks + 1 < 4) {
; #pragma unroll
;                 for (int db = 0; db < NDB; ++db) { vlo[(ks + 1) & 1][db] = vtr(sb + va[db] + (ks + 1) * (16 * ROWB)); vhh[(ks + 1) & 1][db] = vtr(sb + va[db] + (ks + 1) * (16 * ROWB) + 4 * ROWB); }
;             }
; #pragma unroll
;             for (int db = 0; db < NDB; ++db) {
;                 const s16x4 lo = vlo[ks & 1][db], hh = vhh[ks & 1][db];
;                 const bf16x8 vf = (bf16x8){lo[0], lo[1], lo[2], lo[3], hh[0], hh[1], hh[2], hh[3]};
;                 o[db] = __builtin_amdgcn_mfma_f32_32x32x16_bf16(vf, pfs[ks], o[db], 0, 0, 0);
;             }
;             if (ks == 0) ATT_EXP_SLICE(p0, 8, pfs[1]);
;             if (ks == 1) ATT_EXP_SLICE(p1, 0, pfs[2]);
;             if (ks == 2) ATT_EXP_SLICE(p1, 8, pfs[3]);
;         }
.Ldiff_b2_nowait:
	s_barrier
	v_exp_f32_e32 v167, v98
	v_exp_f32_e32 v169, v99
	v_exp_f32_e32 v171, v100
	v_exp_f32_e32 v173, v101
	v_exp_f32_e32 v166, v102
	v_exp_f32_e32 v168, v103
	v_exp_f32_e32 v170, v104
	v_exp_f32_e32 v172, v105
	v_cvt_pk_bf16_f32 v98, v167, v169
	v_cvt_pk_bf16_f32 v99, v171, v173
	v_cvt_pk_bf16_f32 v100, v166, v168
	v_cvt_pk_bf16_f32 v101, v170, v172
	ds_read_b64_tr_b16 v[102:103], v164 offset:20480
	ds_read_b64_tr_b16 v[104:105], v164 offset:21504
	s_setprio 0
	s_waitcnt lgkmcnt(8)
	v_mfma_f32_32x32x16_bf16 v[50:65], v[142:145], v[98:101], v[50:65]
	v_exp_f32_e32 v142, v82
	v_exp_f32_e32 v143, v83
	v_exp_f32_e32 v144, v84
	v_exp_f32_e32 v145, v85
	v_exp_f32_e32 v165, v86
	v_exp_f32_e32 v174, v87
	v_exp_f32_e32 v175, v88
	s_waitcnt lgkmcnt(6)
	v_mfma_f32_32x32x16_bf16 v[34:49], v[138:141], v[98:101], v[34:49]
	v_exp_f32_e32 v139, v110
	v_exp_f32_e32 v141, v111
	v_exp_f32_e32 v138, v112
	v_exp_f32_e32 v140, v113
	v_exp_f32_e32 v176, v89
	v_cvt_pk_bf16_f32 v86, v142, v143
	v_cvt_pk_bf16_f32 v87, v144, v145
	s_waitcnt lgkmcnt(4)
	v_mfma_f32_32x32x16_bf16 v[18:33], v[134:137], v[98:101], v[18:33]
	v_exp_f32_e32 v135, v106
	v_exp_f32_e32 v137, v107
	v_exp_f32_e32 v134, v108
	v_exp_f32_e32 v136, v109
	ds_read_b64_tr_b16 v[106:107], v164 offset:24576
	ds_read_b64_tr_b16 v[108:109], v164 offset:25600
	v_cvt_pk_bf16_f32 v88, v165, v174
	v_cvt_pk_bf16_f32 v89, v175, v176
	s_waitcnt lgkmcnt(4)
	v_mfma_f32_32x32x16_bf16 v[2:17], v[130:133], v[98:101], v[2:17]
	v_cvt_pk_bf16_f32 v98, v135, v137
	v_cvt_pk_bf16_f32 v99, v134, v136
	v_cvt_pk_bf16_f32 v100, v139, v141
	v_cvt_pk_bf16_f32 v101, v138, v140
	v_add_f32_e64 v82, v168, v166
	v_add_f32_e64 v83, v169, v167
	v_exp_f32_e32 v0, v90
	v_exp_f32_e32 v90, v94
	s_waitcnt lgkmcnt(2)
	v_mfma_f32_32x32x16_bf16 v[50:65], v[102:105], v[98:101], v[50:65]
	ds_read_b64_tr_b16 v[102:103], v163 offset:4096
	ds_read_b64_tr_b16 v[104:105], v163 offset:5120
	ds_read_b64_tr_b16 v[110:111], v164 offset:29696
	v_exp_f32_e32 v94, v96
	v_exp_f32_e32 v96, v97
	v_add_f32_e32 v97, v176, v175
	s_add_i32 s7, s6, 0x8000
	s_cmp_lg_u32 s6, 0x18000
	s_cselect_b32 s6, s7, 0
	s_waitcnt lgkmcnt(1)
	v_mfma_f32_32x32x16_bf16 v[34:49], v[102:105], v[98:101], v[34:49]
	ds_read_b64_tr_b16 v[102:103], v161 offset:4096
	ds_read_b64_tr_b16 v[104:105], v161 offset:5120
	ds_read_b64_tr_b16 v[130:131], v161 offset:8192
	ds_read_b64_tr_b16 v[132:133], v161 offset:9216
	s_add_i32 s7, s5, 0x8000
	s_cmp_lg_u32 s5, 0x18000
	s_cselect_b32 s5, s7, 0
	s_add_i32 s4, s4, 1
	s_cmp_lg_u32 s4, 64
	s_waitcnt lgkmcnt(2)
	v_mfma_f32_32x32x16_bf16 v[18:33], v[102:105], v[98:101], v[18:33]
	ds_read_b64_tr_b16 v[102:103], v162 offset:4096
	ds_read_b64_tr_b16 v[104:105], v162 offset:5120
	ds_read_b64_tr_b16 v[84:85], v161 offset:13312
	s_waitcnt lgkmcnt(1)
	v_mfma_f32_32x32x16_bf16 v[2:17], v[102:105], v[98:101], v[2:17]
	v_add_f32_e64 v102, v172, v170
	v_add_f32_e64 v103, v173, v171
	v_add_f32_e64 v82, v102, v82
	v_add_f32_e64 v83, v103, v83
	v_mfma_f32_32x32x16_bf16 v[50:65], v[106:109], v[86:89], v[50:65]
	ds_read_b64_tr_b16 v[98:99], v163 offset:8192
	ds_read_b64_tr_b16 v[100:101], v163 offset:9216
	ds_read_b64_tr_b16 v[108:109], v164 offset:28672
	ds_read_b64_tr_b16 v[102:103], v163 offset:12288
	ds_read_b64_tr_b16 v[104:105], v163 offset:13312
	v_pk_add_f32 v[106:107], v[82:83], v[82:83] op_sel_hi:[0,1]
	v_pk_add_f32 v[82:83], v[136:137], v[134:135]
	v_exp_f32_e32 v106, v91
	v_pk_add_f32 v[112:113], v[82:83], v[82:83] op_sel_hi:[0,1]
	v_pk_add_f32 v[82:83], v[140:141], v[138:139]
	s_waitcnt lgkmcnt(3)
	v_mfma_f32_32x32x16_bf16 v[34:49], v[98:101], v[86:89], v[34:49]
	ds_read_b64_tr_b16 v[98:99], v162 offset:8192
	ds_read_b64_tr_b16 v[100:101], v162 offset:9216
	v_add_f32_e64 v134, v82, v82
	v_add_f32_e64 v135, v82, v83
	v_exp_f32_e32 v112, v92
	v_exp_f32_e32 v134, v93
	v_exp_f32_e32 v92, v95
	v_add_f32_e32 v91, v143, v142
	v_add_f32_e32 v93, v145, v144
	v_mfma_f32_32x32x16_bf16 v[18:33], v[130:133], v[86:89], v[18:33]
	ds_read_b64_tr_b16 v[130:131], v162 offset:12288
	ds_read_b64_tr_b16 v[132:133], v162 offset:13312
	ds_read_b64_tr_b16 v[82:83], v161 offset:12288
	v_add_f32_e32 v95, v174, v165
	s_waitcnt lgkmcnt(3)
	v_mfma_f32_32x32x16_bf16 v[2:17], v[98:101], v[86:89], v[2:17]
	v_cvt_pk_bf16_f32 v86, v0, v106
	v_cvt_pk_bf16_f32 v87, v112, v134
	v_cvt_pk_bf16_f32 v88, v90, v92
	v_cvt_pk_bf16_f32 v89, v94, v96
	v_add_f32_e64 v98, v106, v0
	v_add_f32_e64 v99, v107, v1
	v_pk_add_f32 v[100:101], v[134:135], v[112:113]
	v_pk_add_f32 v[90:91], v[92:93], v[90:91]
	v_mfma_f32_32x32x16_bf16 v[50:65], v[108:111], v[86:89], v[50:65]
	v_add_f32_e64 v92, v96, v94
	v_add_f32_e64 v93, v97, v95
	v_add_f32_e64 v98, v100, v98
	v_add_f32_e64 v99, v101, v99
	v_add_f32_e64 v90, v92, v90
	v_add_f32_e64 v91, v93, v91
	v_pk_add_f32 v[90:91], v[90:91], v[98:99]
	s_nop 0
	v_add_f32_e32 v0, v90, v91
	v_mfma_f32_32x32x16_bf16 v[34:49], v[102:105], v[86:89], v[34:49]
	v_add_f32_e32 v160, v160, v0
	s_waitcnt lgkmcnt(0)
	v_mfma_f32_32x32x16_bf16 v[18:33], v[82:85], v[86:89], v[18:33]
	v_mfma_f32_32x32x16_bf16 v[2:17], v[130:133], v[86:89], v[2:17]
	s_cbranch_scc0 .LBB0_777
